# MLA: more issue bubbles in the older half's softmax segment (every 5 VALU slots)
# speedup vs baseline: 1.0202x; 1.0007x over previous
.Lmla_nowrite_A:
	s_waitcnt lgkmcnt(9)
	v_mfma_f32_32x32x16_bf16 v[64:79], v[178:181], v[100:103], v[64:79]
	s_waitcnt lgkmcnt(8)
	v_mfma_f32_32x32x16_bf16 v[48:63], v[198:201], v[100:103], v[48:63]
	s_setprio 0
	s_nop 10
	v_max_f32_e32 v172, v64, v65
	v_max3_f32 v173, v66, v67, v49
	v_max3_f32 v172, v172, v48, v50
	v_max3_f32 v172, v172, v51, v68
	v_max3_f32 v173, v173, v70, v71
	s_nop 1
	v_max3_f32 v172, v172, v69, v52
	v_max3_f32 v173, v173, v54, v55
	v_max3_f32 v172, v172, v53, v72
	v_max3_f32 v173, v173, v74, v75
	v_max3_f32 v172, v172, v73, v56
	s_nop 1
	v_max3_f32 v173, v173, v58, v59
	v_max3_f32 v172, v172, v57, v76
	v_max3_f32 v173, v173, v78, v79
	v_max3_f32 v172, v172, v77, v60
	v_max3_f32 v173, v173, v62, v63
	s_nop 1
	v_max3_f32 v172, v172, v61, v173
	v_mov_b32_e32 v173, v172
	s_nop 1
	v_permlane32_swap_b32_e32 v172, v173
	v_max_f32_e32 v177, v172, v173
	v_cmp_lt_f32_e32 vcc, s14, v177
	s_nop 1
	s_cbranch_vccz .Lmla_norescale_A
	v_max_f32_e32 v172, s15, v177
	v_max_f32_e32 v173, 0xc2c80000, v172
	v_exp_f32_e64 v173, -v173
	v_add_f32_e32 v156, v156, v172
	s_nop 1
	v_sub_f32_e32 v48, v48, v172
	v_sub_f32_e32 v49, v49, v172
	v_sub_f32_e32 v50, v50, v172
	v_sub_f32_e32 v51, v51, v172
	v_sub_f32_e32 v52, v52, v172
	s_nop 1
	v_sub_f32_e32 v53, v53, v172
	v_sub_f32_e32 v54, v54, v172
	v_sub_f32_e32 v55, v55, v172
	v_sub_f32_e32 v56, v56, v172
	v_sub_f32_e32 v57, v57, v172
	s_nop 1
	v_sub_f32_e32 v58, v58, v172
	v_sub_f32_e32 v59, v59, v172
	v_sub_f32_e32 v60, v60, v172
	v_sub_f32_e32 v61, v61, v172
	v_sub_f32_e32 v62, v62, v172
	s_nop 1
	v_sub_f32_e32 v63, v63, v172
	v_sub_f32_e32 v64, v64, v172
	v_sub_f32_e32 v65, v65, v172
	v_sub_f32_e32 v66, v66, v172
	v_sub_f32_e32 v67, v67, v172
	s_nop 1
	v_sub_f32_e32 v68, v68, v172
	v_sub_f32_e32 v69, v69, v172
	v_sub_f32_e32 v70, v70, v172
	v_sub_f32_e32 v71, v71, v172
	v_sub_f32_e32 v72, v72, v172
	s_nop 1
	v_sub_f32_e32 v73, v73, v172
	v_sub_f32_e32 v74, v74, v172
	v_sub_f32_e32 v75, v75, v172
	v_sub_f32_e32 v76, v76, v172
	v_sub_f32_e32 v77, v77, v172
	s_nop 1
	v_sub_f32_e32 v78, v78, v172
	v_sub_f32_e32 v79, v79, v172
	v_mul_f32_e32 v0, v0, v173
	v_mul_f32_e32 v1, v1, v173
	v_mul_f32_e32 v2, v2, v173
	s_nop 1
	v_mul_f32_e32 v3, v3, v173
	v_mul_f32_e32 v4, v4, v173
	v_mul_f32_e32 v5, v5, v173
	v_mul_f32_e32 v6, v6, v173
	v_mul_f32_e32 v7, v7, v173
	s_nop 1
	v_mul_f32_e32 v8, v8, v173
	v_mul_f32_e32 v9, v9, v173
	v_mul_f32_e32 v10, v10, v173
	v_mul_f32_e32 v11, v11, v173
	v_mul_f32_e32 v12, v12, v173
	s_nop 1
	v_mul_f32_e32 v13, v13, v173
	v_mul_f32_e32 v14, v14, v173
	v_mul_f32_e32 v15, v15, v173
	v_mul_f32_e32 v16, v16, v173
	v_mul_f32_e32 v17, v17, v173
	s_nop 1
	v_mul_f32_e32 v18, v18, v173
	v_mul_f32_e32 v19, v19, v173
	v_mul_f32_e32 v20, v20, v173
	v_mul_f32_e32 v21, v21, v173
	v_mul_f32_e32 v22, v22, v173
	s_nop 1
	v_mul_f32_e32 v23, v23, v173
	v_mul_f32_e32 v24, v24, v173
	v_mul_f32_e32 v25, v25, v173
	v_mul_f32_e32 v26, v26, v173
	v_mul_f32_e32 v27, v27, v173
	s_nop 1
	v_mul_f32_e32 v28, v28, v173
	v_mul_f32_e32 v29, v29, v173
	v_mul_f32_e32 v30, v30, v173
	v_mul_f32_e32 v31, v31, v173
	v_mul_f32_e32 v157, v157, v173
	s_nop 1
	v_sub_f32_e32 v32, 0, v156
	v_mov_b32_e32 v33, v32
	v_mov_b32_e32 v34, v32
	v_mov_b32_e32 v35, v32
	v_mov_b32_e32 v36, v32
	s_nop 1
	v_mov_b32_e32 v37, v32
	v_mov_b32_e32 v38, v32
	v_mov_b32_e32 v39, v32
	v_mov_b32_e32 v40, v32
	v_mov_b32_e32 v41, v32
	s_nop 1
	v_mov_b32_e32 v42, v32
	v_mov_b32_e32 v43, v32
	v_mov_b32_e32 v44, v32
	v_mov_b32_e32 v45, v32
	v_mov_b32_e32 v46, v32
	s_nop 1
	v_mov_b32_e32 v47, v32
.Lmla_norescale_A:
	v_exp_f32_e32 v64, v64
	v_exp_f32_e32 v65, v65
	v_exp_f32_e32 v66, v66
	s_nop 1
	v_exp_f32_e32 v67, v67
	v_exp_f32_e32 v68, v68
	v_exp_f32_e32 v69, v69
	s_nop 1
	v_exp_f32_e32 v70, v70
	v_exp_f32_e32 v71, v71
	v_cvt_pk_bf16_f32 v234, v64, v65
	s_nop 1
	v_cvt_pk_bf16_f32 v235, v66, v67
	v_cvt_pk_bf16_f32 v236, v68, v69
	v_cvt_pk_bf16_f32 v237, v70, v71
	v_exp_f32_e32 v72, v72
	s_nop 1
	v_exp_f32_e32 v73, v73
	v_exp_f32_e32 v74, v74
	v_exp_f32_e32 v75, v75
	s_nop 1
	v_exp_f32_e32 v76, v76
	v_exp_f32_e32 v77, v77
	v_exp_f32_e32 v78, v78
	s_nop 1
	v_exp_f32_e32 v79, v79
	v_cvt_pk_bf16_f32 v238, v72, v73
	v_cvt_pk_bf16_f32 v239, v74, v75
	v_cvt_pk_bf16_f32 v240, v76, v77
	s_nop 1
	v_cvt_pk_bf16_f32 v241, v78, v79
	v_exp_f32_e32 v48, v48
	v_exp_f32_e32 v49, v49
	s_nop 1
	v_exp_f32_e32 v50, v50
	v_exp_f32_e32 v51, v51
	v_exp_f32_e32 v52, v52
	s_nop 1
	v_exp_f32_e32 v53, v53
	v_exp_f32_e32 v54, v54
	v_exp_f32_e32 v55, v55
	s_nop 1
	v_cvt_pk_bf16_f32 v242, v48, v49
	v_cvt_pk_bf16_f32 v243, v50, v51
	v_cvt_pk_bf16_f32 v244, v52, v53
	v_cvt_pk_bf16_f32 v245, v54, v55
	v_exp_f32_e32 v56, v56
	s_nop 1
	v_exp_f32_e32 v57, v57
	v_exp_f32_e32 v58, v58
	v_exp_f32_e32 v59, v59
	s_nop 1
	v_exp_f32_e32 v60, v60
	v_exp_f32_e32 v61, v61
	v_exp_f32_e32 v62, v62
	s_nop 1
	v_exp_f32_e32 v63, v63
	v_cvt_pk_bf16_f32 v246, v56, v57
	v_cvt_pk_bf16_f32 v247, v58, v59
	v_cvt_pk_bf16_f32 v248, v60, v61
	s_nop 1
	v_cvt_pk_bf16_f32 v249, v62, v63
	v_add_f32_e32 v172, v64, v65
	v_add_f32_e32 v173, v66, v67
	v_add_f32_e32 v177, v68, v69
	v_add_f32_e32 v64, v70, v71
	s_nop 1
	v_add_f32_e32 v172, v172, v72
	v_add_f32_e32 v173, v173, v73
	v_add_f32_e32 v177, v177, v74
	v_add_f32_e32 v64, v64, v75
	v_add_f32_e32 v172, v172, v76
	s_nop 1
	v_add_f32_e32 v173, v173, v77
	v_add_f32_e32 v177, v177, v78
	v_add_f32_e32 v64, v64, v79
	v_add_f32_e32 v172, v172, v48
	v_add_f32_e32 v173, v173, v49
	s_nop 1
	v_add_f32_e32 v177, v177, v50
	v_add_f32_e32 v64, v64, v51
	v_add_f32_e32 v172, v172, v52
	v_add_f32_e32 v173, v173, v53
	v_add_f32_e32 v177, v177, v54
	s_nop 1
	v_add_f32_e32 v64, v64, v55
	v_add_f32_e32 v172, v172, v56
	v_add_f32_e32 v173, v173, v57
	v_add_f32_e32 v177, v177, v58
	v_add_f32_e32 v64, v64, v59
	s_nop 1
	v_add_f32_e32 v172, v172, v60
	v_add_f32_e32 v173, v173, v61
	v_add_f32_e32 v177, v177, v62
	v_add_f32_e32 v64, v64, v63
	v_add_f32_e32 v172, v172, v173
	s_nop 1
	v_add_f32_e32 v177, v177, v64
	v_add_f32_e32 v172, v172, v177
	v_add_f32_e32 v157, v157, v172
	s_mov_b32 s14, 0x41000000
	s_mov_b32 s15, 0
	s_waitcnt lgkmcnt(0)
	s_barrier
	s_add_i32 s28, s28, 1
	s_cmp_lt_i32 s28, s22
	s_cbranch_scc1 .Lmla_A_loop
	v_mfma_f32_32x32x16_bf16 v[16:31], v[202:205], v[234:237], v[16:31]
	v_mfma_f32_32x32x16_bf16 v[0:15], v[218:221], v[234:237], v[0:15]
	v_mfma_f32_32x32x16_bf16 v[16:31], v[206:209], v[238:241], v[16:31]
	v_mfma_f32_32x32x16_bf16 v[0:15], v[222:225], v[238:241], v[0:15]
	v_mfma_f32_32x32x16_bf16 v[16:31], v[210:213], v[242:245], v[16:31]
	v_mfma_f32_32x32x16_bf16 v[0:15], v[226:229], v[242:245], v[0:15]
	v_mfma_f32_32x32x16_bf16 v[16:31], v[214:217], v[246:249], v[16:31]
	v_mfma_f32_32x32x16_bf16 v[0:15], v[230:233], v[246:249], v[0:15]
	s_branch .Lmla_exit
